# gate/up epilogue: SwiGLU math re-emitted with packed f32 VALU ops (v_pk_fma/mul/add_f32), in place in dead accumulators; same per-element arithmetic
# baseline (speedup 1.0000x reference)
; #define LAS __attribute__((address_space(3)))
; __device__ __forceinline__ unsigned pk4_fp8(float a, float b, float c, float d) { int w = 0; w = __builtin_amdgcn_cvt_pk_fp8_f32(a, b, w, false); w = __builtin_amdgcn_cvt_pk_fp8_f32(c, d, w, true); return (unsigned)w; }
;     __device__ __forceinline__ void operator()(const f32x4 (&acc)[2][2][4][2], const Unit& u, int wr, int wc, int fr, int fq, const LAS float* lb) const {
;         const int row0 = u.pm * BM + wr * 64 + fr, j0 = u.pn * 128 + wc * 16 + 4 * fq;
;         const float* be = bgu + (size_t)u.e * 2048;
;         f32x4 bg[2], bu[2];
; #pragma unroll
;         for (int bj = 0; bj < 2; ++bj) { bg[bj] = *(const LAS f32x4*)(lb + wc * 16 + 4 * fq + bj * 64); bu[bj] = *(const LAS f32x4*)(lb + 128 + wc * 16 + 4 * fq + bj * 64); }
; #pragma unroll
;         for (int ai = 0; ai < 2; ++ai)
; #pragma unroll
;             for (int m = 0; m < 4; ++m) { unsigned char* rowp = ACT + (size_t)(row0 + ai * HALF + m * 16) * 1024 + j0;
; #pragma unroll
;                 for (int bj = 0; bj < 2; ++bj) { const f32x4 g4 = acc[ai][bj][m][0] * (1.0f / W8_SCALE) + bg[bj], u4 = acc[ai][bj][m][1] * (1.0f / W8_SCALE) + bu[bj]; float o[4];
; #pragma unroll
;                     for (int i = 0; i < 4; ++i) { const float g = fminf(g4[i], 7.0f), up = __builtin_amdgcn_fmed3f(u4[i], -7.0f, 7.0f);
;                         const float rs = __builtin_amdgcn_rcpf(1.0f + __builtin_amdgcn_exp2f(g * -2.45546696f)); o[i] = __builtin_fmaf(up, ACT8_SCALE, ACT8_SCALE) * (g * rs); }
;                     *(unsigned*)(rowp + bj * 64) = pk4_fp8(o[0], o[1], o[2], o[3]); } }
;     }
.LBB0_101:
	v_mov_b32_e32 v0, v168
	s_lshl_b32 s16, s93, 8
	s_lshl_b32 s12, s95, 10
	s_add_i32 s16, s16, s61
	s_and_b32 s12, s12, 0x400
	v_and_or_b32 v18, v0, 15, s16
	v_lshrrev_b32_e32 v0, 2, v0
	v_and_b32_e32 v16, 12, v0
	s_add_i32 s12, s72, s12
	v_lshl_add_u32 v0, v16, 2, s12
	ds_read_b128 v[12:15], v0
	ds_read_b128 v[4:7], v0 offset:256
	ds_read_b128 v[8:11], v0 offset:512
	ds_read_b128 v[0:3], v0 offset:768
	s_lshl_b32 s12, s46, 7
	s_waitcnt lgkmcnt(0)
	s_mov_b32 s98, 0x3c800000
	s_mov_b32 s99, 0xc01d265f
	s_mov_b32 s100, 0x41000000
	s_mov_b32 s101, 0x3f800000
	s_or_b32 s12, s12, s70
	v_or_b32_e32 v16, s12, v16
	v_readlane_b32 s16, v251, 21
	v_ashrrev_i32_e32 v17, 31, v16
	v_readlane_b32 s17, v251, 22
	s_mov_b32 s20, 0xc0e00000
	v_lshl_add_u64 v[20:21], s[16:17], 0, v[16:17]
	v_ashrrev_i32_e32 v19, 31, v18
	v_lshlrev_b64 v[16:17], 10, v[18:19]
	v_lshl_add_u64 v[16:17], v[20:21], 0, v[16:17]
	v_pk_fma_f32 v[160:161], v[160:161], s[98:99], v[12:13] op_sel_hi:[1,0,1]
	v_pk_fma_f32 v[162:163], v[162:163], s[98:99], v[14:15] op_sel_hi:[1,0,1]
	v_pk_fma_f32 v[156:157], v[156:157], s[98:99], v[8:9] op_sel_hi:[1,0,1]
	v_pk_fma_f32 v[158:159], v[158:159], s[98:99], v[10:11] op_sel_hi:[1,0,1]
	v_min_f32_e32 v160, 0x40e00000, v160
	v_min_f32_e32 v161, 0x40e00000, v161
	v_min_f32_e32 v162, 0x40e00000, v162
	v_min_f32_e32 v163, 0x40e00000, v163
	v_med3_f32 v156, v156, s20, v250
	v_med3_f32 v157, v157, s20, v250
	v_med3_f32 v158, v158, s20, v250
	v_med3_f32 v159, v159, s20, v250
	v_pk_mul_f32 v[24:25], v[160:161], s[98:99] op_sel:[0,1] op_sel_hi:[1,1]
	v_pk_mul_f32 v[26:27], v[162:163], s[98:99] op_sel:[0,1] op_sel_hi:[1,1]
	v_exp_f32_e32 v24, v24
	v_exp_f32_e32 v25, v25
	v_exp_f32_e32 v26, v26
	v_exp_f32_e32 v27, v27
	v_pk_fma_f32 v[156:157], v[156:157], s[100:101], s[100:101] op_sel_hi:[1,0,0]
	v_pk_fma_f32 v[158:159], v[158:159], s[100:101], s[100:101] op_sel_hi:[1,0,0]
	v_pk_add_f32 v[24:25], v[24:25], s[100:101] op_sel:[0,1] op_sel_hi:[1,1]
	v_pk_add_f32 v[26:27], v[26:27], s[100:101] op_sel:[0,1] op_sel_hi:[1,1]
	v_rcp_f32_e32 v24, v24
	v_rcp_f32_e32 v25, v25
	v_rcp_f32_e32 v26, v26
	v_rcp_f32_e32 v27, v27
	v_mov_b32_e32 v28, v33
	v_pk_mul_f32 v[24:25], v[160:161], v[24:25]
	v_pk_mul_f32 v[26:27], v[162:163], v[26:27]
	v_pk_mul_f32 v[156:157], v[156:157], v[24:25]
	v_pk_mul_f32 v[158:159], v[158:159], v[26:27]
	v_cvt_pk_fp8_f32 v28, v156, v157
	s_nop 0
	v_cvt_pk_fp8_f32 v28, v158, v159 op_sel:[0,0,1]
	s_nop 0
	global_store_dword v[16:17], v28, off
	v_pk_fma_f32 v[152:153], v[152:153], s[98:99], v[4:5] op_sel_hi:[1,0,1]
	v_pk_fma_f32 v[154:155], v[154:155], s[98:99], v[6:7] op_sel_hi:[1,0,1]
	v_pk_fma_f32 v[148:149], v[148:149], s[98:99], v[0:1] op_sel_hi:[1,0,1]
	v_pk_fma_f32 v[150:151], v[150:151], s[98:99], v[2:3] op_sel_hi:[1,0,1]
	v_min_f32_e32 v152, 0x40e00000, v152
	v_min_f32_e32 v153, 0x40e00000, v153
	v_min_f32_e32 v154, 0x40e00000, v154
	v_min_f32_e32 v155, 0x40e00000, v155
	v_med3_f32 v148, v148, s20, v250
	v_med3_f32 v149, v149, s20, v250
	v_med3_f32 v150, v150, s20, v250
	v_med3_f32 v151, v151, s20, v250
	v_pk_mul_f32 v[24:25], v[152:153], s[98:99] op_sel:[0,1] op_sel_hi:[1,1]
	v_pk_mul_f32 v[26:27], v[154:155], s[98:99] op_sel:[0,1] op_sel_hi:[1,1]
	v_exp_f32_e32 v24, v24
	v_exp_f32_e32 v25, v25
	v_exp_f32_e32 v26, v26
	v_exp_f32_e32 v27, v27
	v_pk_fma_f32 v[148:149], v[148:149], s[100:101], s[100:101] op_sel_hi:[1,0,0]
	v_pk_fma_f32 v[150:151], v[150:151], s[100:101], s[100:101] op_sel_hi:[1,0,0]
	v_pk_add_f32 v[24:25], v[24:25], s[100:101] op_sel:[0,1] op_sel_hi:[1,1]
	v_pk_add_f32 v[26:27], v[26:27], s[100:101] op_sel:[0,1] op_sel_hi:[1,1]
	v_rcp_f32_e32 v24, v24
	v_rcp_f32_e32 v25, v25
	v_rcp_f32_e32 v26, v26
	v_rcp_f32_e32 v27, v27
	v_mov_b32_e32 v30, v33
	v_pk_mul_f32 v[24:25], v[152:153], v[24:25]
	v_pk_mul_f32 v[26:27], v[154:155], v[26:27]
	v_pk_mul_f32 v[148:149], v[148:149], v[24:25]
	v_pk_mul_f32 v[150:151], v[150:151], v[26:27]
	v_cvt_pk_fp8_f32 v30, v148, v149
	s_nop 0
	v_cvt_pk_fp8_f32 v30, v150, v151 op_sel:[0,0,1]
	s_nop 0
	global_store_dword v[16:17], v30, off offset:64
	v_or_b32_e32 v22, 16, v18
	v_ashrrev_i32_e32 v23, 31, v22
	v_lshlrev_b64 v[22:23], 10, v[22:23]
	v_lshl_add_u64 v[22:23], v[20:21], 0, v[22:23]
	v_pk_fma_f32 v[144:145], v[144:145], s[98:99], v[12:13] op_sel_hi:[1,0,1]
	v_pk_fma_f32 v[146:147], v[146:147], s[98:99], v[14:15] op_sel_hi:[1,0,1]
	v_pk_fma_f32 v[140:141], v[140:141], s[98:99], v[8:9] op_sel_hi:[1,0,1]
	v_pk_fma_f32 v[142:143], v[142:143], s[98:99], v[10:11] op_sel_hi:[1,0,1]
	v_min_f32_e32 v144, 0x40e00000, v144
	v_min_f32_e32 v145, 0x40e00000, v145
	v_min_f32_e32 v146, 0x40e00000, v146
	v_min_f32_e32 v147, 0x40e00000, v147
	v_med3_f32 v140, v140, s20, v250
	v_med3_f32 v141, v141, s20, v250
	v_med3_f32 v142, v142, s20, v250
	v_med3_f32 v143, v143, s20, v250
	v_pk_mul_f32 v[24:25], v[144:145], s[98:99] op_sel:[0,1] op_sel_hi:[1,1]
	v_pk_mul_f32 v[26:27], v[146:147], s[98:99] op_sel:[0,1] op_sel_hi:[1,1]
	v_exp_f32_e32 v24, v24
	v_exp_f32_e32 v25, v25
	v_exp_f32_e32 v26, v26
	v_exp_f32_e32 v27, v27
	v_pk_fma_f32 v[140:141], v[140:141], s[100:101], s[100:101] op_sel_hi:[1,0,0]
	v_pk_fma_f32 v[142:143], v[142:143], s[100:101], s[100:101] op_sel_hi:[1,0,0]
	v_pk_add_f32 v[24:25], v[24:25], s[100:101] op_sel:[0,1] op_sel_hi:[1,1]
	v_pk_add_f32 v[26:27], v[26:27], s[100:101] op_sel:[0,1] op_sel_hi:[1,1]
	v_rcp_f32_e32 v24, v24
	v_rcp_f32_e32 v25, v25
	v_rcp_f32_e32 v26, v26
	v_rcp_f32_e32 v27, v27
	v_mov_b32_e32 v28, v33
	v_pk_mul_f32 v[24:25], v[144:145], v[24:25]
	v_pk_mul_f32 v[26:27], v[146:147], v[26:27]
	v_pk_mul_f32 v[140:141], v[140:141], v[24:25]
	v_pk_mul_f32 v[142:143], v[142:143], v[26:27]
; #define LAS __attribute__((address_space(3)))
; __device__ __forceinline__ unsigned pk4_fp8(float a, float b, float c, float d) { int w = 0; w = __builtin_amdgcn_cvt_pk_fp8_f32(a, b, w, false); w = __builtin_amdgcn_cvt_pk_fp8_f32(c, d, w, true); return (unsigned)w; }
;     __device__ __forceinline__ void operator()(const f32x4 (&acc)[2][2][4][2], const Unit& u, int wr, int wc, int fr, int fq, const LAS float* lb) const {
;         const int row0 = u.pm * BM + wr * 64 + fr, j0 = u.pn * 128 + wc * 16 + 4 * fq;
;         const float* be = bgu + (size_t)u.e * 2048;
;         f32x4 bg[2], bu[2];
; #pragma unroll
;         for (int bj = 0; bj < 2; ++bj) { bg[bj] = *(const LAS f32x4*)(lb + wc * 16 + 4 * fq + bj * 64); bu[bj] = *(const LAS f32x4*)(lb + 128 + wc * 16 + 4 * fq + bj * 64); }
; #pragma unroll
;         for (int ai = 0; ai < 2; ++ai)
; #pragma unroll
;             for (int m = 0; m < 4; ++m) { unsigned char* rowp = ACT + (size_t)(row0 + ai * HALF + m * 16) * 1024 + j0;
; #pragma unroll
;                 for (int bj = 0; bj < 2; ++bj) { const f32x4 g4 = acc[ai][bj][m][0] * (1.0f / W8_SCALE) + bg[bj], u4 = acc[ai][bj][m][1] * (1.0f / W8_SCALE) + bu[bj]; float o[4];
; #pragma unroll
;                     for (int i = 0; i < 4; ++i) { const float g = fminf(g4[i], 7.0f), up = __builtin_amdgcn_fmed3f(u4[i], -7.0f, 7.0f);
;                         const float rs = __builtin_amdgcn_rcpf(1.0f + __builtin_amdgcn_exp2f(g * -2.45546696f)); o[i] = __builtin_fmaf(up, ACT8_SCALE, ACT8_SCALE) * (g * rs); }
;                     *(unsigned*)(rowp + bj * 64) = pk4_fp8(o[0], o[1], o[2], o[3]); } }
;     }
	v_cvt_pk_fp8_f32 v28, v140, v141
	s_nop 0
	v_cvt_pk_fp8_f32 v28, v142, v143 op_sel:[0,0,1]
	s_nop 0
	global_store_dword v[22:23], v28, off
	v_pk_fma_f32 v[136:137], v[136:137], s[98:99], v[4:5] op_sel_hi:[1,0,1]
	v_pk_fma_f32 v[138:139], v[138:139], s[98:99], v[6:7] op_sel_hi:[1,0,1]
	v_pk_fma_f32 v[132:133], v[132:133], s[98:99], v[0:1] op_sel_hi:[1,0,1]
	v_pk_fma_f32 v[134:135], v[134:135], s[98:99], v[2:3] op_sel_hi:[1,0,1]
	v_min_f32_e32 v136, 0x40e00000, v136
	v_min_f32_e32 v137, 0x40e00000, v137
	v_min_f32_e32 v138, 0x40e00000, v138
	v_min_f32_e32 v139, 0x40e00000, v139
	v_med3_f32 v132, v132, s20, v250
	v_med3_f32 v133, v133, s20, v250
	v_med3_f32 v134, v134, s20, v250
	v_med3_f32 v135, v135, s20, v250
	v_pk_mul_f32 v[24:25], v[136:137], s[98:99] op_sel:[0,1] op_sel_hi:[1,1]
	v_pk_mul_f32 v[26:27], v[138:139], s[98:99] op_sel:[0,1] op_sel_hi:[1,1]
	v_exp_f32_e32 v24, v24
	v_exp_f32_e32 v25, v25
	v_exp_f32_e32 v26, v26
	v_exp_f32_e32 v27, v27
	v_pk_fma_f32 v[132:133], v[132:133], s[100:101], s[100:101] op_sel_hi:[1,0,0]
	v_pk_fma_f32 v[134:135], v[134:135], s[100:101], s[100:101] op_sel_hi:[1,0,0]
	v_pk_add_f32 v[24:25], v[24:25], s[100:101] op_sel:[0,1] op_sel_hi:[1,1]
	v_pk_add_f32 v[26:27], v[26:27], s[100:101] op_sel:[0,1] op_sel_hi:[1,1]
	v_rcp_f32_e32 v24, v24
	v_rcp_f32_e32 v25, v25
	v_rcp_f32_e32 v26, v26
	v_rcp_f32_e32 v27, v27
	v_mov_b32_e32 v30, v33
	v_pk_mul_f32 v[24:25], v[136:137], v[24:25]
	v_pk_mul_f32 v[26:27], v[138:139], v[26:27]
	v_pk_mul_f32 v[132:133], v[132:133], v[24:25]
	v_pk_mul_f32 v[134:135], v[134:135], v[26:27]
	v_cvt_pk_fp8_f32 v30, v132, v133
	s_nop 0
	v_cvt_pk_fp8_f32 v30, v134, v135 op_sel:[0,0,1]
	s_nop 0
	global_store_dword v[22:23], v30, off offset:64
	v_or_b32_e32 v22, 32, v18
	v_ashrrev_i32_e32 v23, 31, v22
	v_lshlrev_b64 v[22:23], 10, v[22:23]
	v_lshl_add_u64 v[22:23], v[20:21], 0, v[22:23]
	v_pk_fma_f32 v[128:129], v[128:129], s[98:99], v[12:13] op_sel_hi:[1,0,1]
	v_pk_fma_f32 v[130:131], v[130:131], s[98:99], v[14:15] op_sel_hi:[1,0,1]
	v_pk_fma_f32 v[124:125], v[124:125], s[98:99], v[8:9] op_sel_hi:[1,0,1]
	v_pk_fma_f32 v[126:127], v[126:127], s[98:99], v[10:11] op_sel_hi:[1,0,1]
	v_min_f32_e32 v128, 0x40e00000, v128
	v_min_f32_e32 v129, 0x40e00000, v129
	v_min_f32_e32 v130, 0x40e00000, v130
	v_min_f32_e32 v131, 0x40e00000, v131
	v_med3_f32 v124, v124, s20, v250
	v_med3_f32 v125, v125, s20, v250
	v_med3_f32 v126, v126, s20, v250
	v_med3_f32 v127, v127, s20, v250
	v_pk_mul_f32 v[24:25], v[128:129], s[98:99] op_sel:[0,1] op_sel_hi:[1,1]
	v_pk_mul_f32 v[26:27], v[130:131], s[98:99] op_sel:[0,1] op_sel_hi:[1,1]
	v_exp_f32_e32 v24, v24
	v_exp_f32_e32 v25, v25
	v_exp_f32_e32 v26, v26
	v_exp_f32_e32 v27, v27
	v_pk_fma_f32 v[124:125], v[124:125], s[100:101], s[100:101] op_sel_hi:[1,0,0]
	v_pk_fma_f32 v[126:127], v[126:127], s[100:101], s[100:101] op_sel_hi:[1,0,0]
	v_pk_add_f32 v[24:25], v[24:25], s[100:101] op_sel:[0,1] op_sel_hi:[1,1]
	v_pk_add_f32 v[26:27], v[26:27], s[100:101] op_sel:[0,1] op_sel_hi:[1,1]
	v_rcp_f32_e32 v24, v24
	v_rcp_f32_e32 v25, v25
	v_rcp_f32_e32 v26, v26
	v_rcp_f32_e32 v27, v27
	v_mov_b32_e32 v28, v33
	v_pk_mul_f32 v[24:25], v[128:129], v[24:25]
	v_pk_mul_f32 v[26:27], v[130:131], v[26:27]
	v_pk_mul_f32 v[124:125], v[124:125], v[24:25]
	v_pk_mul_f32 v[126:127], v[126:127], v[26:27]
	v_cvt_pk_fp8_f32 v28, v124, v125
	s_nop 0
	v_cvt_pk_fp8_f32 v28, v126, v127 op_sel:[0,0,1]
	s_nop 0
	global_store_dword v[22:23], v28, off
	v_pk_fma_f32 v[120:121], v[120:121], s[98:99], v[4:5] op_sel_hi:[1,0,1]
	v_pk_fma_f32 v[122:123], v[122:123], s[98:99], v[6:7] op_sel_hi:[1,0,1]
	v_pk_fma_f32 v[116:117], v[116:117], s[98:99], v[0:1] op_sel_hi:[1,0,1]
	v_pk_fma_f32 v[118:119], v[118:119], s[98:99], v[2:3] op_sel_hi:[1,0,1]
	v_min_f32_e32 v120, 0x40e00000, v120
	v_min_f32_e32 v121, 0x40e00000, v121
	v_min_f32_e32 v122, 0x40e00000, v122
	v_min_f32_e32 v123, 0x40e00000, v123
	v_med3_f32 v116, v116, s20, v250
	v_med3_f32 v117, v117, s20, v250
	v_med3_f32 v118, v118, s20, v250
	v_med3_f32 v119, v119, s20, v250
	v_pk_mul_f32 v[24:25], v[120:121], s[98:99] op_sel:[0,1] op_sel_hi:[1,1]
	v_pk_mul_f32 v[26:27], v[122:123], s[98:99] op_sel:[0,1] op_sel_hi:[1,1]
	v_exp_f32_e32 v24, v24
	v_exp_f32_e32 v25, v25
	v_exp_f32_e32 v26, v26
	v_exp_f32_e32 v27, v27
	v_pk_fma_f32 v[116:117], v[116:117], s[100:101], s[100:101] op_sel_hi:[1,0,0]
	v_pk_fma_f32 v[118:119], v[118:119], s[100:101], s[100:101] op_sel_hi:[1,0,0]
	v_pk_add_f32 v[24:25], v[24:25], s[100:101] op_sel:[0,1] op_sel_hi:[1,1]
	v_pk_add_f32 v[26:27], v[26:27], s[100:101] op_sel:[0,1] op_sel_hi:[1,1]
	v_rcp_f32_e32 v24, v24
	v_rcp_f32_e32 v25, v25
	v_rcp_f32_e32 v26, v26
	v_rcp_f32_e32 v27, v27
	v_mov_b32_e32 v30, v33
	v_pk_mul_f32 v[24:25], v[120:121], v[24:25]
	v_pk_mul_f32 v[26:27], v[122:123], v[26:27]
	v_pk_mul_f32 v[116:117], v[116:117], v[24:25]
	v_pk_mul_f32 v[118:119], v[118:119], v[26:27]
	v_cvt_pk_fp8_f32 v30, v116, v117
	s_nop 0
	v_cvt_pk_fp8_f32 v30, v118, v119 op_sel:[0,0,1]
	s_nop 0
	global_store_dword v[22:23], v30, off offset:64
	v_or_b32_e32 v18, 48, v18
	v_ashrrev_i32_e32 v19, 31, v18
	v_lshlrev_b64 v[18:19], 10, v[18:19]
	v_lshl_add_u64 v[18:19], v[20:21], 0, v[18:19]
	v_pk_fma_f32 v[112:113], v[112:113], s[98:99], v[12:13] op_sel_hi:[1,0,1]
	v_pk_fma_f32 v[114:115], v[114:115], s[98:99], v[14:15] op_sel_hi:[1,0,1]
	v_pk_fma_f32 v[108:109], v[108:109], s[98:99], v[8:9] op_sel_hi:[1,0,1]
	v_pk_fma_f32 v[110:111], v[110:111], s[98:99], v[10:11] op_sel_hi:[1,0,1]
	v_min_f32_e32 v112, 0x40e00000, v112
	v_min_f32_e32 v113, 0x40e00000, v113
	v_min_f32_e32 v114, 0x40e00000, v114
	v_min_f32_e32 v115, 0x40e00000, v115
; #define LAS __attribute__((address_space(3)))
; __device__ __forceinline__ unsigned pk4_fp8(float a, float b, float c, float d) { int w = 0; w = __builtin_amdgcn_cvt_pk_fp8_f32(a, b, w, false); w = __builtin_amdgcn_cvt_pk_fp8_f32(c, d, w, true); return (unsigned)w; }
;     __device__ __forceinline__ void operator()(const f32x4 (&acc)[2][2][4][2], const Unit& u, int wr, int wc, int fr, int fq, const LAS float* lb) const {
;         const int row0 = u.pm * BM + wr * 64 + fr, j0 = u.pn * 128 + wc * 16 + 4 * fq;
;         const float* be = bgu + (size_t)u.e * 2048;
;         f32x4 bg[2], bu[2];
; #pragma unroll
;         for (int bj = 0; bj < 2; ++bj) { bg[bj] = *(const LAS f32x4*)(lb + wc * 16 + 4 * fq + bj * 64); bu[bj] = *(const LAS f32x4*)(lb + 128 + wc * 16 + 4 * fq + bj * 64); }
; #pragma unroll
;         for (int ai = 0; ai < 2; ++ai)
; #pragma unroll
;             for (int m = 0; m < 4; ++m) { unsigned char* rowp = ACT + (size_t)(row0 + ai * HALF + m * 16) * 1024 + j0;
; #pragma unroll
;                 for (int bj = 0; bj < 2; ++bj) { const f32x4 g4 = acc[ai][bj][m][0] * (1.0f / W8_SCALE) + bg[bj], u4 = acc[ai][bj][m][1] * (1.0f / W8_SCALE) + bu[bj]; float o[4];
; #pragma unroll
;                     for (int i = 0; i < 4; ++i) { const float g = fminf(g4[i], 7.0f), up = __builtin_amdgcn_fmed3f(u4[i], -7.0f, 7.0f);
;                         const float rs = __builtin_amdgcn_rcpf(1.0f + __builtin_amdgcn_exp2f(g * -2.45546696f)); o[i] = __builtin_fmaf(up, ACT8_SCALE, ACT8_SCALE) * (g * rs); }
;                     *(unsigned*)(rowp + bj * 64) = pk4_fp8(o[0], o[1], o[2], o[3]); } }
;     }
	v_med3_f32 v108, v108, s20, v250
	v_med3_f32 v109, v109, s20, v250
	v_med3_f32 v110, v110, s20, v250
	v_med3_f32 v111, v111, s20, v250
	v_pk_mul_f32 v[24:25], v[112:113], s[98:99] op_sel:[0,1] op_sel_hi:[1,1]
	v_pk_mul_f32 v[26:27], v[114:115], s[98:99] op_sel:[0,1] op_sel_hi:[1,1]
	v_exp_f32_e32 v24, v24
	v_exp_f32_e32 v25, v25
	v_exp_f32_e32 v26, v26
	v_exp_f32_e32 v27, v27
	v_pk_fma_f32 v[108:109], v[108:109], s[100:101], s[100:101] op_sel_hi:[1,0,0]
	v_pk_fma_f32 v[110:111], v[110:111], s[100:101], s[100:101] op_sel_hi:[1,0,0]
	v_pk_add_f32 v[24:25], v[24:25], s[100:101] op_sel:[0,1] op_sel_hi:[1,1]
	v_pk_add_f32 v[26:27], v[26:27], s[100:101] op_sel:[0,1] op_sel_hi:[1,1]
	v_rcp_f32_e32 v24, v24
	v_rcp_f32_e32 v25, v25
	v_rcp_f32_e32 v26, v26
	v_rcp_f32_e32 v27, v27
	v_mov_b32_e32 v28, v33
	v_pk_mul_f32 v[24:25], v[112:113], v[24:25]
	v_pk_mul_f32 v[26:27], v[114:115], v[26:27]
	v_pk_mul_f32 v[108:109], v[108:109], v[24:25]
	v_pk_mul_f32 v[110:111], v[110:111], v[26:27]
	v_cvt_pk_fp8_f32 v28, v108, v109
	s_nop 0
	v_cvt_pk_fp8_f32 v28, v110, v111 op_sel:[0,0,1]
	s_nop 0
	global_store_dword v[18:19], v28, off
	v_pk_fma_f32 v[104:105], v[104:105], s[98:99], v[4:5] op_sel_hi:[1,0,1]
	v_pk_fma_f32 v[106:107], v[106:107], s[98:99], v[6:7] op_sel_hi:[1,0,1]
	v_pk_fma_f32 v[100:101], v[100:101], s[98:99], v[0:1] op_sel_hi:[1,0,1]
	v_pk_fma_f32 v[102:103], v[102:103], s[98:99], v[2:3] op_sel_hi:[1,0,1]
	v_min_f32_e32 v104, 0x40e00000, v104
	v_min_f32_e32 v105, 0x40e00000, v105
	v_min_f32_e32 v106, 0x40e00000, v106
	v_min_f32_e32 v107, 0x40e00000, v107
	v_med3_f32 v100, v100, s20, v250
	v_med3_f32 v101, v101, s20, v250
	v_med3_f32 v102, v102, s20, v250
	v_med3_f32 v103, v103, s20, v250
	v_pk_mul_f32 v[24:25], v[104:105], s[98:99] op_sel:[0,1] op_sel_hi:[1,1]
	v_pk_mul_f32 v[26:27], v[106:107], s[98:99] op_sel:[0,1] op_sel_hi:[1,1]
	v_exp_f32_e32 v24, v24
	v_exp_f32_e32 v25, v25
	v_exp_f32_e32 v26, v26
	v_exp_f32_e32 v27, v27
	v_pk_fma_f32 v[100:101], v[100:101], s[100:101], s[100:101] op_sel_hi:[1,0,0]
	v_pk_fma_f32 v[102:103], v[102:103], s[100:101], s[100:101] op_sel_hi:[1,0,0]
	v_pk_add_f32 v[24:25], v[24:25], s[100:101] op_sel:[0,1] op_sel_hi:[1,1]
	v_pk_add_f32 v[26:27], v[26:27], s[100:101] op_sel:[0,1] op_sel_hi:[1,1]
	v_rcp_f32_e32 v24, v24
	v_rcp_f32_e32 v25, v25
	v_rcp_f32_e32 v26, v26
	v_rcp_f32_e32 v27, v27
	v_mov_b32_e32 v30, v33
	v_pk_mul_f32 v[24:25], v[104:105], v[24:25]
	v_pk_mul_f32 v[26:27], v[106:107], v[26:27]
	v_pk_mul_f32 v[100:101], v[100:101], v[24:25]
	v_pk_mul_f32 v[102:103], v[102:103], v[26:27]
	v_cvt_pk_fp8_f32 v30, v100, v101
	s_nop 0
	v_cvt_pk_fp8_f32 v30, v102, v103 op_sel:[0,0,1]
	s_nop 0
	global_store_dword v[18:19], v30, off offset:64
	s_mov_b32 s12, 0x20000
	v_add_co_u32_e32 v20, vcc, s12, v16
	s_mov_b64 s[16:17], 0x20000
	s_nop 0
	v_addc_co_u32_e32 v21, vcc, 0, v17, vcc
	v_lshl_add_u64 v[18:19], v[16:17], 0, s[16:17]
	v_pk_fma_f32 v[96:97], v[96:97], s[98:99], v[12:13] op_sel_hi:[1,0,1]
	v_pk_fma_f32 v[98:99], v[98:99], s[98:99], v[14:15] op_sel_hi:[1,0,1]
	v_pk_fma_f32 v[92:93], v[92:93], s[98:99], v[8:9] op_sel_hi:[1,0,1]
	v_pk_fma_f32 v[94:95], v[94:95], s[98:99], v[10:11] op_sel_hi:[1,0,1]
	v_min_f32_e32 v96, 0x40e00000, v96
	v_min_f32_e32 v97, 0x40e00000, v97
	v_min_f32_e32 v98, 0x40e00000, v98
	v_min_f32_e32 v99, 0x40e00000, v99
	v_med3_f32 v92, v92, s20, v250
	v_med3_f32 v93, v93, s20, v250
	v_med3_f32 v94, v94, s20, v250
	v_med3_f32 v95, v95, s20, v250
	v_pk_mul_f32 v[24:25], v[96:97], s[98:99] op_sel:[0,1] op_sel_hi:[1,1]
	v_pk_mul_f32 v[26:27], v[98:99], s[98:99] op_sel:[0,1] op_sel_hi:[1,1]
	v_exp_f32_e32 v24, v24
	v_exp_f32_e32 v25, v25
	v_exp_f32_e32 v26, v26
	v_exp_f32_e32 v27, v27
	v_pk_fma_f32 v[92:93], v[92:93], s[100:101], s[100:101] op_sel_hi:[1,0,0]
	v_pk_fma_f32 v[94:95], v[94:95], s[100:101], s[100:101] op_sel_hi:[1,0,0]
	v_pk_add_f32 v[24:25], v[24:25], s[100:101] op_sel:[0,1] op_sel_hi:[1,1]
	v_pk_add_f32 v[26:27], v[26:27], s[100:101] op_sel:[0,1] op_sel_hi:[1,1]
	v_rcp_f32_e32 v24, v24
	v_rcp_f32_e32 v25, v25
	v_rcp_f32_e32 v26, v26
	v_rcp_f32_e32 v27, v27
	v_mov_b32_e32 v28, v33
	v_pk_mul_f32 v[24:25], v[96:97], v[24:25]
	v_pk_mul_f32 v[26:27], v[98:99], v[26:27]
	v_pk_mul_f32 v[92:93], v[92:93], v[24:25]
	v_pk_mul_f32 v[94:95], v[94:95], v[26:27]
	v_cvt_pk_fp8_f32 v28, v92, v93
	s_nop 0
	v_cvt_pk_fp8_f32 v28, v94, v95 op_sel:[0,0,1]
	s_nop 0
	global_store_dword v[20:21], v28, off
	v_pk_fma_f32 v[88:89], v[88:89], s[98:99], v[4:5] op_sel_hi:[1,0,1]
	v_pk_fma_f32 v[90:91], v[90:91], s[98:99], v[6:7] op_sel_hi:[1,0,1]
	v_pk_fma_f32 v[84:85], v[84:85], s[98:99], v[0:1] op_sel_hi:[1,0,1]
	v_pk_fma_f32 v[86:87], v[86:87], s[98:99], v[2:3] op_sel_hi:[1,0,1]
	v_min_f32_e32 v88, 0x40e00000, v88
	v_min_f32_e32 v89, 0x40e00000, v89
	v_min_f32_e32 v90, 0x40e00000, v90
	v_min_f32_e32 v91, 0x40e00000, v91
	v_med3_f32 v84, v84, s20, v250
	v_med3_f32 v85, v85, s20, v250
	v_med3_f32 v86, v86, s20, v250
	v_med3_f32 v87, v87, s20, v250
	v_pk_mul_f32 v[24:25], v[88:89], s[98:99] op_sel:[0,1] op_sel_hi:[1,1]
	v_pk_mul_f32 v[26:27], v[90:91], s[98:99] op_sel:[0,1] op_sel_hi:[1,1]
	v_exp_f32_e32 v24, v24
	v_exp_f32_e32 v25, v25
	v_exp_f32_e32 v26, v26
	v_exp_f32_e32 v27, v27
	v_pk_fma_f32 v[84:85], v[84:85], s[100:101], s[100:101] op_sel_hi:[1,0,0]
	v_pk_fma_f32 v[86:87], v[86:87], s[100:101], s[100:101] op_sel_hi:[1,0,0]
	v_pk_add_f32 v[24:25], v[24:25], s[100:101] op_sel:[0,1] op_sel_hi:[1,1]
	v_pk_add_f32 v[26:27], v[26:27], s[100:101] op_sel:[0,1] op_sel_hi:[1,1]
	v_rcp_f32_e32 v24, v24
	v_rcp_f32_e32 v25, v25
	v_rcp_f32_e32 v26, v26
	v_rcp_f32_e32 v27, v27
	v_mov_b32_e32 v30, v33
; #define LAS __attribute__((address_space(3)))
; __device__ __forceinline__ unsigned pk4_fp8(float a, float b, float c, float d) { int w = 0; w = __builtin_amdgcn_cvt_pk_fp8_f32(a, b, w, false); w = __builtin_amdgcn_cvt_pk_fp8_f32(c, d, w, true); return (unsigned)w; }
;     __device__ __forceinline__ void operator()(const f32x4 (&acc)[2][2][4][2], const Unit& u, int wr, int wc, int fr, int fq, const LAS float* lb) const {
;         const int row0 = u.pm * BM + wr * 64 + fr, j0 = u.pn * 128 + wc * 16 + 4 * fq;
;         const float* be = bgu + (size_t)u.e * 2048;
;         f32x4 bg[2], bu[2];
; #pragma unroll
;         for (int bj = 0; bj < 2; ++bj) { bg[bj] = *(const LAS f32x4*)(lb + wc * 16 + 4 * fq + bj * 64); bu[bj] = *(const LAS f32x4*)(lb + 128 + wc * 16 + 4 * fq + bj * 64); }
; #pragma unroll
;         for (int ai = 0; ai < 2; ++ai)
; #pragma unroll
;             for (int m = 0; m < 4; ++m) { unsigned char* rowp = ACT + (size_t)(row0 + ai * HALF + m * 16) * 1024 + j0;
; #pragma unroll
;                 for (int bj = 0; bj < 2; ++bj) { const f32x4 g4 = acc[ai][bj][m][0] * (1.0f / W8_SCALE) + bg[bj], u4 = acc[ai][bj][m][1] * (1.0f / W8_SCALE) + bu[bj]; float o[4];
; #pragma unroll
;                     for (int i = 0; i < 4; ++i) { const float g = fminf(g4[i], 7.0f), up = __builtin_amdgcn_fmed3f(u4[i], -7.0f, 7.0f);
;                         const float rs = __builtin_amdgcn_rcpf(1.0f + __builtin_amdgcn_exp2f(g * -2.45546696f)); o[i] = __builtin_fmaf(up, ACT8_SCALE, ACT8_SCALE) * (g * rs); }
;                     *(unsigned*)(rowp + bj * 64) = pk4_fp8(o[0], o[1], o[2], o[3]); } }
;     }
	v_pk_mul_f32 v[24:25], v[88:89], v[24:25]
	v_pk_mul_f32 v[26:27], v[90:91], v[26:27]
	v_pk_mul_f32 v[84:85], v[84:85], v[24:25]
	v_pk_mul_f32 v[86:87], v[86:87], v[26:27]
	v_cvt_pk_fp8_f32 v30, v84, v85
	s_nop 0
	v_cvt_pk_fp8_f32 v30, v86, v87 op_sel:[0,0,1]
	s_nop 0
	global_store_dword v[18:19], v30, off offset:64
	v_add_co_u32_e32 v20, vcc, s21, v16
	s_mov_b64 s[16:17], 0x24000
	v_addc_co_u32_e32 v21, vcc, 0, v17, vcc
	v_lshl_add_u64 v[18:19], v[16:17], 0, s[16:17]
	v_pk_fma_f32 v[80:81], v[80:81], s[98:99], v[12:13] op_sel_hi:[1,0,1]
	v_pk_fma_f32 v[82:83], v[82:83], s[98:99], v[14:15] op_sel_hi:[1,0,1]
	v_pk_fma_f32 v[76:77], v[76:77], s[98:99], v[8:9] op_sel_hi:[1,0,1]
	v_pk_fma_f32 v[78:79], v[78:79], s[98:99], v[10:11] op_sel_hi:[1,0,1]
	v_min_f32_e32 v80, 0x40e00000, v80
	v_min_f32_e32 v81, 0x40e00000, v81
	v_min_f32_e32 v82, 0x40e00000, v82
	v_min_f32_e32 v83, 0x40e00000, v83
	v_med3_f32 v76, v76, s20, v250
	v_med3_f32 v77, v77, s20, v250
	v_med3_f32 v78, v78, s20, v250
	v_med3_f32 v79, v79, s20, v250
	v_pk_mul_f32 v[24:25], v[80:81], s[98:99] op_sel:[0,1] op_sel_hi:[1,1]
	v_pk_mul_f32 v[26:27], v[82:83], s[98:99] op_sel:[0,1] op_sel_hi:[1,1]
	v_exp_f32_e32 v24, v24
	v_exp_f32_e32 v25, v25
	v_exp_f32_e32 v26, v26
	v_exp_f32_e32 v27, v27
	v_pk_fma_f32 v[76:77], v[76:77], s[100:101], s[100:101] op_sel_hi:[1,0,0]
	v_pk_fma_f32 v[78:79], v[78:79], s[100:101], s[100:101] op_sel_hi:[1,0,0]
	v_pk_add_f32 v[24:25], v[24:25], s[100:101] op_sel:[0,1] op_sel_hi:[1,1]
	v_pk_add_f32 v[26:27], v[26:27], s[100:101] op_sel:[0,1] op_sel_hi:[1,1]
	v_rcp_f32_e32 v24, v24
	v_rcp_f32_e32 v25, v25
	v_rcp_f32_e32 v26, v26
	v_rcp_f32_e32 v27, v27
	v_mov_b32_e32 v28, v33
	v_pk_mul_f32 v[24:25], v[80:81], v[24:25]
	v_pk_mul_f32 v[26:27], v[82:83], v[26:27]
	v_pk_mul_f32 v[76:77], v[76:77], v[24:25]
	v_pk_mul_f32 v[78:79], v[78:79], v[26:27]
	v_cvt_pk_fp8_f32 v28, v76, v77
	s_nop 0
	v_cvt_pk_fp8_f32 v28, v78, v79 op_sel:[0,0,1]
	s_nop 0
	global_store_dword v[20:21], v28, off
	v_pk_fma_f32 v[72:73], v[72:73], s[98:99], v[4:5] op_sel_hi:[1,0,1]
	v_pk_fma_f32 v[74:75], v[74:75], s[98:99], v[6:7] op_sel_hi:[1,0,1]
	v_pk_fma_f32 v[68:69], v[68:69], s[98:99], v[0:1] op_sel_hi:[1,0,1]
	v_pk_fma_f32 v[70:71], v[70:71], s[98:99], v[2:3] op_sel_hi:[1,0,1]
	v_min_f32_e32 v72, 0x40e00000, v72
	v_min_f32_e32 v73, 0x40e00000, v73
	v_min_f32_e32 v74, 0x40e00000, v74
	v_min_f32_e32 v75, 0x40e00000, v75
	v_med3_f32 v68, v68, s20, v250
	v_med3_f32 v69, v69, s20, v250
	v_med3_f32 v70, v70, s20, v250
	v_med3_f32 v71, v71, s20, v250
	v_pk_mul_f32 v[24:25], v[72:73], s[98:99] op_sel:[0,1] op_sel_hi:[1,1]
	v_pk_mul_f32 v[26:27], v[74:75], s[98:99] op_sel:[0,1] op_sel_hi:[1,1]
	v_exp_f32_e32 v24, v24
	v_exp_f32_e32 v25, v25
	v_exp_f32_e32 v26, v26
	v_exp_f32_e32 v27, v27
	v_pk_fma_f32 v[68:69], v[68:69], s[100:101], s[100:101] op_sel_hi:[1,0,0]
	v_pk_fma_f32 v[70:71], v[70:71], s[100:101], s[100:101] op_sel_hi:[1,0,0]
	v_pk_add_f32 v[24:25], v[24:25], s[100:101] op_sel:[0,1] op_sel_hi:[1,1]
	v_pk_add_f32 v[26:27], v[26:27], s[100:101] op_sel:[0,1] op_sel_hi:[1,1]
	v_rcp_f32_e32 v24, v24
	v_rcp_f32_e32 v25, v25
	v_rcp_f32_e32 v26, v26
	v_rcp_f32_e32 v27, v27
	v_mov_b32_e32 v30, v33
	v_pk_mul_f32 v[24:25], v[72:73], v[24:25]
	v_pk_mul_f32 v[26:27], v[74:75], v[26:27]
	v_pk_mul_f32 v[68:69], v[68:69], v[24:25]
	v_pk_mul_f32 v[70:71], v[70:71], v[26:27]
	v_cvt_pk_fp8_f32 v30, v68, v69
	s_nop 0
	v_cvt_pk_fp8_f32 v30, v70, v71 op_sel:[0,0,1]
	s_nop 0
	global_store_dword v[18:19], v30, off offset:64
	s_mov_b32 s12, 0x28000
	v_add_co_u32_e32 v20, vcc, s12, v16
	s_mov_b64 s[16:17], 0x28000
	s_nop 0
	v_addc_co_u32_e32 v21, vcc, 0, v17, vcc
	v_lshl_add_u64 v[18:19], v[16:17], 0, s[16:17]
	v_pk_fma_f32 v[64:65], v[64:65], s[98:99], v[12:13] op_sel_hi:[1,0,1]
	v_pk_fma_f32 v[66:67], v[66:67], s[98:99], v[14:15] op_sel_hi:[1,0,1]
	v_pk_fma_f32 v[60:61], v[60:61], s[98:99], v[8:9] op_sel_hi:[1,0,1]
	v_pk_fma_f32 v[62:63], v[62:63], s[98:99], v[10:11] op_sel_hi:[1,0,1]
	v_min_f32_e32 v64, 0x40e00000, v64
	v_min_f32_e32 v65, 0x40e00000, v65
	v_min_f32_e32 v66, 0x40e00000, v66
	v_min_f32_e32 v67, 0x40e00000, v67
	v_med3_f32 v60, v60, s20, v250
	v_med3_f32 v61, v61, s20, v250
	v_med3_f32 v62, v62, s20, v250
	v_med3_f32 v63, v63, s20, v250
	v_pk_mul_f32 v[24:25], v[64:65], s[98:99] op_sel:[0,1] op_sel_hi:[1,1]
	v_pk_mul_f32 v[26:27], v[66:67], s[98:99] op_sel:[0,1] op_sel_hi:[1,1]
	v_exp_f32_e32 v24, v24
	v_exp_f32_e32 v25, v25
	v_exp_f32_e32 v26, v26
	v_exp_f32_e32 v27, v27
	v_pk_fma_f32 v[60:61], v[60:61], s[100:101], s[100:101] op_sel_hi:[1,0,0]
	v_pk_fma_f32 v[62:63], v[62:63], s[100:101], s[100:101] op_sel_hi:[1,0,0]
	v_pk_add_f32 v[24:25], v[24:25], s[100:101] op_sel:[0,1] op_sel_hi:[1,1]
	v_pk_add_f32 v[26:27], v[26:27], s[100:101] op_sel:[0,1] op_sel_hi:[1,1]
	v_rcp_f32_e32 v24, v24
	v_rcp_f32_e32 v25, v25
	v_rcp_f32_e32 v26, v26
	v_rcp_f32_e32 v27, v27
	v_mov_b32_e32 v28, v33
	v_pk_mul_f32 v[24:25], v[64:65], v[24:25]
	v_pk_mul_f32 v[26:27], v[66:67], v[26:27]
	v_pk_mul_f32 v[60:61], v[60:61], v[24:25]
	v_pk_mul_f32 v[62:63], v[62:63], v[26:27]
	v_cvt_pk_fp8_f32 v28, v60, v61
; #define LAS __attribute__((address_space(3)))
; __device__ __forceinline__ unsigned pk4_fp8(float a, float b, float c, float d) { int w = 0; w = __builtin_amdgcn_cvt_pk_fp8_f32(a, b, w, false); w = __builtin_amdgcn_cvt_pk_fp8_f32(c, d, w, true); return (unsigned)w; }
; #define PG8_BAR __builtin_amdgcn_s_barrier()
; template <bool GATHER, bool FP8, class Epi, class Sched>
; __device__ __forceinline__ void gemm_phase(LAS unsigned char* lds, const int tid, const int K, const Sched& S, const Epi& E) {
;     ...
;         if (wr == 0) PG8_BAR;
;         { int t2 = tid; asm volatile("" : "+v"(t2)); const int l2 = t2 & 63; E(acc, cur, wr, wc, l2 & 15, l2 >> 4, (const LAS float*)(lds + BIAS_OFF + (ui & 1) * 1024)); }
;         if (!has_next) break;
; #pragma unroll
;         for (int a = 0; a < 2; ++a)
; #pragma unroll
;             for (int b = 0; b < 2; ++b)
; #pragma unroll
;                 for (int m = 0; m < 4; ++m)
; #pragma unroll
;                     for (int n = 0; n < 2; ++n) acc[a][b][m][n] = (f32x4){zf, zf, zf, zf};
;         cur = nxt; cA = nA; cB = nB; ++ui;
; #pragma unroll
;         for (int _h = 0; _h < 2; ++_h)
; #pragma unroll
;             for (int _i = 0; _i < 2; ++_i) oC[_h][_i] = o2[_h][_i];
;         if (wr == 1) PG8_BAR;
;     __device__ __forceinline__ void operator()(const f32x4 (&acc)[2][2][4][2], const Unit& u, int wr, int wc, int fr, int fq, const LAS float* lb) const {
;     ...
;             for (int m = 0; m < 4; ++m) { unsigned char* rowp = ACT + (size_t)(row0 + ai * HALF + m * 16) * 1024 + j0;
; #pragma unroll
;                 for (int bj = 0; bj < 2; ++bj) { const f32x4 g4 = acc[ai][bj][m][0] * (1.0f / W8_SCALE) + bg[bj], u4 = acc[ai][bj][m][1] * (1.0f / W8_SCALE) + bu[bj]; float o[4];
; #pragma unroll
;                     for (int i = 0; i < 4; ++i) { const float g = fminf(g4[i], 7.0f), up = __builtin_amdgcn_fmed3f(u4[i], -7.0f, 7.0f);
;                         const float rs = __builtin_amdgcn_rcpf(1.0f + __builtin_amdgcn_exp2f(g * -2.45546696f)); o[i] = __builtin_fmaf(up, ACT8_SCALE, ACT8_SCALE) * (g * rs); }
;                     *(unsigned*)(rowp + bj * 64) = pk4_fp8(o[0], o[1], o[2], o[3]); } }
;     }
	s_nop 0
	v_cvt_pk_fp8_f32 v28, v62, v63 op_sel:[0,0,1]
	s_nop 0
	global_store_dword v[20:21], v28, off
	v_pk_fma_f32 v[56:57], v[56:57], s[98:99], v[4:5] op_sel_hi:[1,0,1]
	v_pk_fma_f32 v[58:59], v[58:59], s[98:99], v[6:7] op_sel_hi:[1,0,1]
	v_pk_fma_f32 v[52:53], v[52:53], s[98:99], v[0:1] op_sel_hi:[1,0,1]
	v_pk_fma_f32 v[54:55], v[54:55], s[98:99], v[2:3] op_sel_hi:[1,0,1]
	v_min_f32_e32 v56, 0x40e00000, v56
	v_min_f32_e32 v57, 0x40e00000, v57
	v_min_f32_e32 v58, 0x40e00000, v58
	v_min_f32_e32 v59, 0x40e00000, v59
	v_med3_f32 v52, v52, s20, v250
	v_med3_f32 v53, v53, s20, v250
	v_med3_f32 v54, v54, s20, v250
	v_med3_f32 v55, v55, s20, v250
	v_pk_mul_f32 v[24:25], v[56:57], s[98:99] op_sel:[0,1] op_sel_hi:[1,1]
	v_pk_mul_f32 v[26:27], v[58:59], s[98:99] op_sel:[0,1] op_sel_hi:[1,1]
	v_exp_f32_e32 v24, v24
	v_exp_f32_e32 v25, v25
	v_exp_f32_e32 v26, v26
	v_exp_f32_e32 v27, v27
	v_pk_fma_f32 v[52:53], v[52:53], s[100:101], s[100:101] op_sel_hi:[1,0,0]
	v_pk_fma_f32 v[54:55], v[54:55], s[100:101], s[100:101] op_sel_hi:[1,0,0]
	v_pk_add_f32 v[24:25], v[24:25], s[100:101] op_sel:[0,1] op_sel_hi:[1,1]
	v_pk_add_f32 v[26:27], v[26:27], s[100:101] op_sel:[0,1] op_sel_hi:[1,1]
	v_rcp_f32_e32 v24, v24
	v_rcp_f32_e32 v25, v25
	v_rcp_f32_e32 v26, v26
	v_rcp_f32_e32 v27, v27
	v_mov_b32_e32 v30, v33
	v_pk_mul_f32 v[24:25], v[56:57], v[24:25]
	v_pk_mul_f32 v[26:27], v[58:59], v[26:27]
	v_pk_mul_f32 v[52:53], v[52:53], v[24:25]
	v_pk_mul_f32 v[54:55], v[54:55], v[26:27]
	v_cvt_pk_fp8_f32 v30, v52, v53
	s_nop 0
	v_cvt_pk_fp8_f32 v30, v54, v55 op_sel:[0,0,1]
	s_nop 0
	global_store_dword v[18:19], v30, off offset:64
	s_mov_b32 s12, 0x2c000
	v_pk_fma_f32 v[48:49], v[48:49], s[98:99], v[12:13] op_sel_hi:[1,0,1]
	v_pk_fma_f32 v[50:51], v[50:51], s[98:99], v[14:15] op_sel_hi:[1,0,1]
	v_pk_fma_f32 v[44:45], v[44:45], s[98:99], v[8:9] op_sel_hi:[1,0,1]
	v_pk_fma_f32 v[46:47], v[46:47], s[98:99], v[10:11] op_sel_hi:[1,0,1]
	v_min_f32_e32 v48, 0x40e00000, v48
	v_min_f32_e32 v49, 0x40e00000, v49
	v_min_f32_e32 v50, 0x40e00000, v50
	v_min_f32_e32 v51, 0x40e00000, v51
	v_med3_f32 v44, v44, s20, v250
	v_med3_f32 v45, v45, s20, v250
	v_med3_f32 v46, v46, s20, v250
	v_med3_f32 v47, v47, s20, v250
	v_pk_mul_f32 v[24:25], v[48:49], s[98:99] op_sel:[0,1] op_sel_hi:[1,1]
	v_pk_mul_f32 v[26:27], v[50:51], s[98:99] op_sel:[0,1] op_sel_hi:[1,1]
	v_exp_f32_e32 v24, v24
	v_exp_f32_e32 v25, v25
	v_exp_f32_e32 v26, v26
	v_exp_f32_e32 v27, v27
	v_pk_fma_f32 v[44:45], v[44:45], s[100:101], s[100:101] op_sel_hi:[1,0,0]
	v_pk_fma_f32 v[46:47], v[46:47], s[100:101], s[100:101] op_sel_hi:[1,0,0]
	v_pk_add_f32 v[24:25], v[24:25], s[100:101] op_sel:[0,1] op_sel_hi:[1,1]
	v_pk_add_f32 v[26:27], v[26:27], s[100:101] op_sel:[0,1] op_sel_hi:[1,1]
	v_rcp_f32_e32 v24, v24
	v_rcp_f32_e32 v25, v25
	v_rcp_f32_e32 v26, v26
	v_rcp_f32_e32 v27, v27
	v_mov_b32_e32 v28, v33
	v_pk_mul_f32 v[24:25], v[48:49], v[24:25]
	v_pk_mul_f32 v[26:27], v[50:51], v[26:27]
	v_pk_mul_f32 v[44:45], v[44:45], v[24:25]
	v_pk_mul_f32 v[46:47], v[46:47], v[26:27]
	v_cvt_pk_fp8_f32 v28, v44, v45
	s_nop 0
	v_cvt_pk_fp8_f32 v28, v46, v47 op_sel:[0,0,1]
	s_nop 0
	v_pk_fma_f32 v[40:41], v[40:41], s[98:99], v[4:5] op_sel_hi:[1,0,1]
	v_pk_fma_f32 v[42:43], v[42:43], s[98:99], v[6:7] op_sel_hi:[1,0,1]
	v_pk_fma_f32 v[34:35], v[34:35], s[98:99], v[0:1] op_sel_hi:[1,0,1]
	v_pk_fma_f32 v[36:37], v[36:37], s[98:99], v[2:3] op_sel_hi:[1,0,1]
	v_min_f32_e32 v40, 0x40e00000, v40
	v_min_f32_e32 v41, 0x40e00000, v41
	v_min_f32_e32 v42, 0x40e00000, v42
	v_min_f32_e32 v43, 0x40e00000, v43
	v_med3_f32 v34, v34, s20, v250
	v_med3_f32 v35, v35, s20, v250
	v_med3_f32 v36, v36, s20, v250
	v_med3_f32 v37, v37, s20, v250
	v_pk_mul_f32 v[24:25], v[40:41], s[98:99] op_sel:[0,1] op_sel_hi:[1,1]
	v_pk_mul_f32 v[26:27], v[42:43], s[98:99] op_sel:[0,1] op_sel_hi:[1,1]
	v_exp_f32_e32 v24, v24
	v_exp_f32_e32 v25, v25
	v_exp_f32_e32 v26, v26
	v_exp_f32_e32 v27, v27
	v_pk_fma_f32 v[34:35], v[34:35], s[100:101], s[100:101] op_sel_hi:[1,0,0]
	v_pk_fma_f32 v[36:37], v[36:37], s[100:101], s[100:101] op_sel_hi:[1,0,0]
	v_pk_add_f32 v[24:25], v[24:25], s[100:101] op_sel:[0,1] op_sel_hi:[1,1]
	v_pk_add_f32 v[26:27], v[26:27], s[100:101] op_sel:[0,1] op_sel_hi:[1,1]
	v_rcp_f32_e32 v24, v24
	v_rcp_f32_e32 v25, v25
	v_rcp_f32_e32 v26, v26
	v_rcp_f32_e32 v27, v27
	v_mov_b32_e32 v30, v33
	v_pk_mul_f32 v[24:25], v[40:41], v[24:25]
	v_pk_mul_f32 v[26:27], v[42:43], v[26:27]
	v_pk_mul_f32 v[34:35], v[34:35], v[24:25]
	v_pk_mul_f32 v[36:37], v[36:37], v[26:27]
	v_cvt_pk_fp8_f32 v30, v34, v35
	s_nop 0
	v_cvt_pk_fp8_f32 v30, v36, v37 op_sel:[0,0,1]
	s_nop 0
	v_add_co_u32_e32 v0, vcc, s12, v16
	s_mov_b64 s[16:17], 0x2c000
	s_nop 0
	v_addc_co_u32_e32 v1, vcc, 0, v17, vcc
	s_andn2_b64 vcc, exec, s[44:45]
	s_mov_b64 s[20:21], -1
	v_mov_b64_e32 v[166:167], 0x5ff
	v_lshl_add_u64 v[18:19], v[16:17], 0, s[16:17]
	global_store_dword v[0:1], v28, off
	global_store_dword v[18:19], v30, off offset:64
	s_cbranch_vccnz .LBB0_86
	v_readlane_b32 s16, v249, 54
	v_readlane_b32 s17, v249, 55
	s_andn2_b64 vcc, exec, s[16:17]
	s_cbranch_vccnz .LBB0_85
	s_barrier
	s_branch .LBB0_85
